# P5 merged and P6 xg bf16 stores written through (sc1) as well
# baseline (speedup 1.0000x reference)
.LBB0_992:
	v_mov_b32_e32 v138, v192
	s_lshl_b32 s2, s2, 8
	s_lshl_b32 s3, s3, 8
	v_lshrrev_b32_e32 v139, 1, v138
	s_add_i32 s2, s2, s54
	v_and_or_b32 v139, v139, 24, s3
	v_and_or_b32 v150, v138, 15, s2
	v_or_b32_e32 v140, s55, v139
	s_cmp_lg_u32 s66, 0
	v_ashrrev_i32_e32 v151, 31, v150
	s_cselect_b64 s[2:3], -1, 0
	s_cmp_eq_u32 s66, 0
	v_ashrrev_i32_e32 v141, 31, v140
	v_lshlrev_b64 v[146:147], 13, v[150:151]
	v_or_b32_e32 v144, 16, v150
	v_or_b32_e32 v142, 32, v150
	v_or_b32_e32 v138, 48, v150
	s_cbranch_scc1 .LBB0_1000
	v_readlane_b32 s44, v254, 49
	v_readlane_b32 s45, v254, 50
	v_lshlrev_b64 v[148:149], 1, v[140:141]
	v_ashrrev_i32_e32 v145, 31, v144
	v_lshl_add_u64 v[154:155], s[44:45], 0, v[146:147]
	v_lshl_add_u64 v[158:159], v[154:155], 0, v[148:149]
	v_add_co_u32_e32 v154, vcc, 0x1000, v158
	v_lshlrev_b64 v[162:163], 13, v[144:145]
	s_nop 0
	v_addc_co_u32_e32 v155, vcc, 0, v159, vcc
	v_lshl_add_u64 v[158:159], v[158:159], 0, s[24:25]
	v_lshl_add_u64 v[162:163], s[44:45], 0, v[162:163]
	global_load_dwordx4 v[154:157], v[154:155], off
	v_lshl_add_u64 v[166:167], v[162:163], 0, v[148:149]
	global_load_dwordx4 v[158:161], v[158:159], off offset:256
	v_add_co_u32_e32 v162, vcc, s60, v166
	v_ashrrev_i32_e32 v143, 31, v142
	s_nop 0
	v_addc_co_u32_e32 v163, vcc, 0, v167, vcc
	global_load_dwordx4 v[162:165], v[162:163], off
	v_readlane_b32 s42, v254, 45
	v_ashrrev_i32_e32 v139, 31, v138
	v_lshlrev_b64 v[170:171], 12, v[150:151]
	v_lshlrev_b64 v[172:173], 13, v[142:143]
	v_readlane_b32 s43, v254, 46
	v_lshl_add_u64 v[166:167], v[166:167], 0, s[24:25]
	v_lshlrev_b64 v[174:175], 13, v[138:139]
	v_lshl_add_u64 v[170:171], s[42:43], 0, v[170:171]
	v_lshl_add_u64 v[172:173], s[44:45], 0, v[172:173]
	global_load_dwordx4 v[166:169], v[166:167], off offset:256
	v_lshl_add_u64 v[174:175], s[44:45], 0, v[174:175]
	v_lshl_add_u64 v[188:189], v[170:171], 0, v[148:149]
	v_lshl_add_u64 v[170:171], v[172:173], 0, v[148:149]
	v_lshl_add_u64 v[178:179], v[174:175], 0, v[148:149]
	v_lshl_add_u64 v[174:175], v[170:171], 0, s[24:25]
	v_add_co_u32_e32 v170, vcc, s60, v170
	global_load_dwordx4 v[174:177], v[174:175], off offset:256
	s_nop 0
	v_addc_co_u32_e32 v171, vcc, 0, v171, vcc
	global_load_dwordx4 v[170:173], v[170:171], off
	v_lshl_add_u64 v[182:183], v[178:179], 0, s[24:25]
	v_add_co_u32_e32 v178, vcc, s60, v178
	v_lshlrev_b64 v[186:187], 12, v[144:145]
	s_nop 0
	v_addc_co_u32_e32 v179, vcc, 0, v179, vcc
	global_load_dwordx4 v[178:181], v[178:179], off
	s_nop 0
	global_load_dwordx4 v[182:185], v[182:183], off offset:256
	s_waitcnt vmcnt(0)
	v_lshlrev_b32_e32 v190, 16, v154
	v_and_b32_e32 v191, 0xffff0000, v154
	v_lshlrev_b32_e32 v194, 16, v156
	v_and_b32_e32 v195, 0xffff0000, v156
	v_lshlrev_b32_e32 v154, 16, v155
	v_and_b32_e32 v155, 0xffff0000, v155
	v_lshlrev_b32_e32 v156, 16, v157
	v_and_b32_e32 v157, 0xffff0000, v157
	v_lshlrev_b32_e32 v196, 16, v158
	v_and_b32_e32 v197, 0xffff0000, v158
	v_lshlrev_b32_e32 v158, 16, v159
	v_and_b32_e32 v159, 0xffff0000, v159
	v_lshlrev_b32_e32 v198, 16, v160
	v_and_b32_e32 v199, 0xffff0000, v160
	v_lshlrev_b32_e32 v160, 16, v161
	v_and_b32_e32 v161, 0xffff0000, v161
	v_pk_mul_f32 v[190:191], v[124:125], v[190:191]
	v_pk_mul_f32 v[194:195], v[120:121], v[194:195]
	v_pk_mul_f32 v[200:201], v[126:127], v[154:155]
	v_pk_mul_f32 v[202:203], v[122:123], v[156:157]
	v_pk_mul_f32 v[196:197], v[92:93], v[196:197]
	v_pk_mul_f32 v[204:205], v[94:95], v[158:159]
	v_pk_mul_f32 v[198:199], v[88:89], v[198:199]
	v_pk_mul_f32 v[206:207], v[90:91], v[160:161]
	v_cvt_pk_bf16_f32 v154, v190, v191
	v_cvt_pk_bf16_f32 v155, v200, v201
	v_cvt_pk_bf16_f32 v156, v194, v195
	v_cvt_pk_bf16_f32 v157, v202, v203
	v_cvt_pk_bf16_f32 v158, v196, v197
	v_cvt_pk_bf16_f32 v159, v204, v205
	v_cvt_pk_bf16_f32 v160, v198, v199
	v_cvt_pk_bf16_f32 v161, v206, v207
	v_lshlrev_b32_e32 v190, 16, v162
	v_and_b32_e32 v191, 0xffff0000, v162
	global_store_dwordx4 v[188:189], v[154:157], off sc1
	global_store_dwordx4 v[188:189], v[158:161], off offset:256 sc1
	v_lshlrev_b32_e32 v162, 16, v169
	v_pk_mul_f32 v[154:155], v[116:117], v[190:191]
	v_lshlrev_b32_e32 v158, 16, v163
	v_and_b32_e32 v159, 0xffff0000, v163
	v_lshlrev_b32_e32 v156, 16, v164
	v_and_b32_e32 v157, 0xffff0000, v164
	v_pk_mul_f32 v[158:159], v[118:119], v[158:159]
	v_lshlrev_b32_e32 v160, 16, v165
	v_and_b32_e32 v161, 0xffff0000, v165
	v_pk_mul_f32 v[156:157], v[112:113], v[156:157]
	v_pk_mul_f32 v[160:161], v[114:115], v[160:161]
	v_cvt_pk_bf16_f32 v154, v154, v155
	v_cvt_pk_bf16_f32 v155, v158, v159
	v_lshl_add_u64 v[158:159], s[42:43], 0, v[186:187]
	v_cvt_pk_bf16_f32 v156, v156, v157
	v_cvt_pk_bf16_f32 v157, v160, v161
	v_lshl_add_u64 v[158:159], v[158:159], 0, v[148:149]
	global_store_dwordx4 v[158:159], v[154:157], off sc1
	v_lshlrev_b32_e32 v160, 16, v167
	v_and_b32_e32 v161, 0xffff0000, v167
	v_lshlrev_b32_e32 v154, 16, v166
	v_and_b32_e32 v155, 0xffff0000, v166
	v_lshlrev_b32_e32 v156, 16, v168
	v_and_b32_e32 v157, 0xffff0000, v168
	v_and_b32_e32 v163, 0xffff0000, v169
	v_pk_mul_f32 v[154:155], v[84:85], v[154:155]
	v_pk_mul_f32 v[156:157], v[80:81], v[156:157]
	v_pk_mul_f32 v[160:161], v[86:87], v[160:161]
	v_pk_mul_f32 v[162:163], v[82:83], v[162:163]
	v_cvt_pk_bf16_f32 v154, v154, v155
	v_cvt_pk_bf16_f32 v155, v160, v161
	v_cvt_pk_bf16_f32 v156, v156, v157
	v_cvt_pk_bf16_f32 v157, v162, v163
	global_store_dwordx4 v[158:159], v[154:157], off offset:256 sc1
	v_lshlrev_b64 v[158:159], 12, v[142:143]
	v_lshlrev_b32_e32 v160, 16, v171
	v_lshlrev_b32_e32 v154, 16, v170
	v_and_b32_e32 v155, 0xffff0000, v170
	v_lshlrev_b32_e32 v156, 16, v172
	v_and_b32_e32 v157, 0xffff0000, v172
	v_and_b32_e32 v161, 0xffff0000, v171
	v_lshlrev_b32_e32 v162, 16, v173
	v_and_b32_e32 v163, 0xffff0000, v173
	v_pk_mul_f32 v[154:155], v[108:109], v[154:155]
	v_pk_mul_f32 v[156:157], v[104:105], v[156:157]
	v_pk_mul_f32 v[160:161], v[110:111], v[160:161]
	v_pk_mul_f32 v[162:163], v[106:107], v[162:163]
	v_lshl_add_u64 v[158:159], s[42:43], 0, v[158:159]
	v_cvt_pk_bf16_f32 v154, v154, v155
	v_cvt_pk_bf16_f32 v155, v160, v161
	v_cvt_pk_bf16_f32 v156, v156, v157
	v_cvt_pk_bf16_f32 v157, v162, v163
	v_lshl_add_u64 v[158:159], v[158:159], 0, v[148:149]
	global_store_dwordx4 v[158:159], v[154:157], off sc1
	v_lshlrev_b32_e32 v160, 16, v175
	v_and_b32_e32 v161, 0xffff0000, v175
	v_lshlrev_b32_e32 v154, 16, v174
	v_and_b32_e32 v155, 0xffff0000, v174
	v_lshlrev_b32_e32 v156, 16, v176
	v_and_b32_e32 v157, 0xffff0000, v176
	v_lshlrev_b32_e32 v162, 16, v177
	v_and_b32_e32 v163, 0xffff0000, v177
	v_pk_mul_f32 v[154:155], v[76:77], v[154:155]
	v_pk_mul_f32 v[156:157], v[72:73], v[156:157]
	v_pk_mul_f32 v[160:161], v[78:79], v[160:161]
	v_pk_mul_f32 v[162:163], v[74:75], v[162:163]
	v_cvt_pk_bf16_f32 v154, v154, v155
	v_cvt_pk_bf16_f32 v155, v160, v161
	v_cvt_pk_bf16_f32 v156, v156, v157
	v_cvt_pk_bf16_f32 v157, v162, v163
	global_store_dwordx4 v[158:159], v[154:157], off offset:256 sc1
	v_lshlrev_b64 v[158:159], 12, v[138:139]
	v_lshlrev_b32_e32 v160, 16, v179
	v_lshlrev_b32_e32 v154, 16, v178
	v_and_b32_e32 v155, 0xffff0000, v178
	v_lshlrev_b32_e32 v156, 16, v180
	v_and_b32_e32 v157, 0xffff0000, v180
	v_and_b32_e32 v161, 0xffff0000, v179
	v_lshlrev_b32_e32 v162, 16, v181
	v_and_b32_e32 v163, 0xffff0000, v181
	v_pk_mul_f32 v[154:155], v[100:101], v[154:155]
	v_pk_mul_f32 v[156:157], v[96:97], v[156:157]
	v_pk_mul_f32 v[160:161], v[102:103], v[160:161]
	v_pk_mul_f32 v[162:163], v[98:99], v[162:163]
	v_lshl_add_u64 v[158:159], s[42:43], 0, v[158:159]
	v_cvt_pk_bf16_f32 v154, v154, v155
	v_cvt_pk_bf16_f32 v155, v160, v161
	v_cvt_pk_bf16_f32 v156, v156, v157
	v_cvt_pk_bf16_f32 v157, v162, v163
	v_lshl_add_u64 v[158:159], v[158:159], 0, v[148:149]
	global_store_dwordx4 v[158:159], v[154:157], off sc1
	v_lshlrev_b32_e32 v160, 16, v183
	v_and_b32_e32 v161, 0xffff0000, v183
	v_lshlrev_b32_e32 v154, 16, v182
	v_and_b32_e32 v155, 0xffff0000, v182
	v_lshlrev_b32_e32 v156, 16, v184
	v_and_b32_e32 v157, 0xffff0000, v184
	v_lshlrev_b32_e32 v162, 16, v185
	v_and_b32_e32 v163, 0xffff0000, v185
	v_pk_mul_f32 v[154:155], v[68:69], v[154:155]
	v_pk_mul_f32 v[156:157], v[64:65], v[156:157]
	v_pk_mul_f32 v[160:161], v[70:71], v[160:161]
	v_pk_mul_f32 v[162:163], v[66:67], v[162:163]
	v_cvt_pk_bf16_f32 v154, v154, v155
	v_cvt_pk_bf16_f32 v155, v160, v161
	v_cvt_pk_bf16_f32 v156, v156, v157
	v_cvt_pk_bf16_f32 v157, v162, v163
	global_store_dwordx4 v[158:159], v[154:157], off offset:256 sc1
	v_add_u32_e32 v170, 0x80, v150
	v_ashrrev_i32_e32 v171, 31, v170
	v_lshlrev_b64 v[154:155], 13, v[170:171]
	v_lshl_add_u64 v[154:155], s[44:45], 0, v[154:155]
	v_add_u32_e32 v172, 0x90, v150
	v_lshl_add_u64 v[158:159], v[154:155], 0, v[148:149]
	v_ashrrev_i32_e32 v173, 31, v172
	v_add_co_u32_e32 v154, vcc, s60, v158
	v_lshlrev_b64 v[162:163], 13, v[172:173]
	s_nop 0
	v_addc_co_u32_e32 v155, vcc, 0, v159, vcc
	v_lshl_add_u64 v[162:163], s[44:45], 0, v[162:163]
	global_load_dwordx4 v[154:157], v[154:155], off
	v_lshl_add_u64 v[158:159], v[158:159], 0, s[24:25]
	v_lshl_add_u64 v[166:167], v[162:163], 0, v[148:149]
	global_load_dwordx4 v[158:161], v[158:159], off offset:256
	v_add_co_u32_e32 v162, vcc, s60, v166
	v_add_u32_e32 v186, 0xa0, v150
	s_nop 0
	v_addc_co_u32_e32 v163, vcc, 0, v167, vcc
	global_load_dwordx4 v[162:165], v[162:163], off
	v_ashrrev_i32_e32 v187, 31, v186
	v_lshlrev_b64 v[174:175], 13, v[186:187]
	v_lshl_add_u64 v[166:167], v[166:167], 0, s[24:25]
	v_lshlrev_b64 v[170:171], 12, v[170:171]
	v_lshlrev_b64 v[188:189], 12, v[172:173]
	v_lshl_add_u64 v[172:173], s[44:45], 0, v[174:175]
	v_add_u32_e32 v150, 0xb0, v150
	global_load_dwordx4 v[166:169], v[166:167], off offset:256
	v_lshl_add_u64 v[170:171], s[42:43], 0, v[170:171]
	v_lshl_add_u64 v[172:173], v[172:173], 0, v[148:149]
	v_ashrrev_i32_e32 v151, 31, v150
	v_lshl_add_u64 v[190:191], v[170:171], 0, v[148:149]
	v_add_co_u32_e32 v170, vcc, s60, v172
	v_lshlrev_b64 v[176:177], 13, v[150:151]
	s_nop 0
	v_addc_co_u32_e32 v171, vcc, 0, v173, vcc
	v_lshl_add_u64 v[174:175], s[44:45], 0, v[176:177]
	v_lshl_add_u64 v[176:177], v[172:173], 0, s[24:25]
	global_load_dwordx4 v[170:173], v[170:171], off
	v_lshl_add_u64 v[174:175], v[174:175], 0, v[148:149]
	v_add_co_u32_e32 v178, vcc, s60, v174
	v_lshl_add_u64 v[182:183], v[174:175], 0, s[24:25]
	s_nop 0
	v_addc_co_u32_e32 v179, vcc, 0, v175, vcc
	global_load_dwordx4 v[174:177], v[176:177], off offset:256
	s_nop 0
	global_load_dwordx4 v[178:181], v[178:179], off
	s_nop 0
	global_load_dwordx4 v[182:185], v[182:183], off offset:256
	v_lshlrev_b64 v[150:151], 12, v[150:151]
	v_lshl_add_u64 v[150:151], s[42:43], 0, v[150:151]
	s_waitcnt vmcnt(7)
	v_lshlrev_b32_e32 v194, 16, v154
	v_and_b32_e32 v195, 0xffff0000, v154
	v_lshlrev_b32_e32 v196, 16, v156
	v_and_b32_e32 v197, 0xffff0000, v156
	v_lshlrev_b32_e32 v154, 16, v155
	v_and_b32_e32 v155, 0xffff0000, v155
	v_lshlrev_b32_e32 v156, 16, v157
	v_and_b32_e32 v157, 0xffff0000, v157
	s_waitcnt vmcnt(6)
	v_lshlrev_b32_e32 v198, 16, v158
	v_and_b32_e32 v199, 0xffff0000, v158
	v_lshlrev_b32_e32 v200, 16, v160
	v_and_b32_e32 v201, 0xffff0000, v160
	v_lshlrev_b32_e32 v158, 16, v159
	v_and_b32_e32 v159, 0xffff0000, v159
	v_lshlrev_b32_e32 v160, 16, v161
	v_and_b32_e32 v161, 0xffff0000, v161
	v_pk_mul_f32 v[194:195], v[60:61], v[194:195]
	v_pk_mul_f32 v[196:197], v[56:57], v[196:197]
	v_pk_mul_f32 v[206:207], v[62:63], v[154:155]
	v_pk_mul_f32 v[208:209], v[58:59], v[156:157]
	v_pk_mul_f32 v[198:199], v[28:29], v[198:199]
	v_pk_mul_f32 v[200:201], v[24:25], v[200:201]
	v_pk_mul_f32 v[210:211], v[30:31], v[158:159]
	v_pk_mul_f32 v[212:213], v[26:27], v[160:161]
	v_cvt_pk_bf16_f32 v154, v194, v195
	v_cvt_pk_bf16_f32 v155, v206, v207
	v_cvt_pk_bf16_f32 v156, v196, v197
	v_cvt_pk_bf16_f32 v157, v208, v209
	v_cvt_pk_bf16_f32 v158, v198, v199
	v_cvt_pk_bf16_f32 v159, v210, v211
	v_cvt_pk_bf16_f32 v160, v200, v201
	v_cvt_pk_bf16_f32 v161, v212, v213
	global_store_dwordx4 v[190:191], v[154:157], off sc1
	global_store_dwordx4 v[190:191], v[158:161], off offset:256 sc1
	s_waitcnt vmcnt(7)
	v_lshlrev_b32_e32 v202, 16, v162
	v_lshlrev_b32_e32 v154, 16, v163
	v_and_b32_e32 v155, 0xffff0000, v163
	v_and_b32_e32 v203, 0xffff0000, v162
	v_lshlrev_b32_e32 v204, 16, v164
	v_and_b32_e32 v205, 0xffff0000, v164
	v_pk_mul_f32 v[158:159], v[54:55], v[154:155]
	v_lshlrev_b32_e32 v154, 16, v165
	v_and_b32_e32 v155, 0xffff0000, v165
	v_pk_mul_f32 v[202:203], v[52:53], v[202:203]
	v_pk_mul_f32 v[156:157], v[48:49], v[204:205]
	v_pk_mul_f32 v[160:161], v[50:51], v[154:155]
	v_cvt_pk_bf16_f32 v155, v158, v159
	v_lshl_add_u64 v[158:159], s[42:43], 0, v[188:189]
	v_cvt_pk_bf16_f32 v154, v202, v203
	v_cvt_pk_bf16_f32 v156, v156, v157
	v_cvt_pk_bf16_f32 v157, v160, v161
	v_lshl_add_u64 v[158:159], v[158:159], 0, v[148:149]
	global_store_dwordx4 v[158:159], v[154:157], off sc1
	s_waitcnt vmcnt(7)
	v_lshlrev_b32_e32 v160, 16, v167
	v_and_b32_e32 v161, 0xffff0000, v167
	v_lshlrev_b32_e32 v154, 16, v166
	v_and_b32_e32 v155, 0xffff0000, v166
	v_lshlrev_b32_e32 v156, 16, v168
	v_and_b32_e32 v157, 0xffff0000, v168
	v_lshlrev_b32_e32 v162, 16, v169
	v_and_b32_e32 v163, 0xffff0000, v169
	v_pk_mul_f32 v[154:155], v[20:21], v[154:155]
	v_pk_mul_f32 v[156:157], v[16:17], v[156:157]
	v_pk_mul_f32 v[160:161], v[22:23], v[160:161]
	v_pk_mul_f32 v[162:163], v[18:19], v[162:163]
	v_cvt_pk_bf16_f32 v154, v154, v155
	v_cvt_pk_bf16_f32 v155, v160, v161
	v_cvt_pk_bf16_f32 v156, v156, v157
	v_cvt_pk_bf16_f32 v157, v162, v163
	global_store_dwordx4 v[158:159], v[154:157], off offset:256 sc1
	v_lshlrev_b64 v[158:159], 12, v[186:187]
	s_waitcnt vmcnt(7)
	v_lshlrev_b32_e32 v160, 16, v171
	v_lshlrev_b32_e32 v154, 16, v170
	v_and_b32_e32 v155, 0xffff0000, v170
	v_lshlrev_b32_e32 v156, 16, v172
	v_and_b32_e32 v157, 0xffff0000, v172
	v_and_b32_e32 v161, 0xffff0000, v171
	v_lshlrev_b32_e32 v162, 16, v173
	v_and_b32_e32 v163, 0xffff0000, v173
	v_pk_mul_f32 v[154:155], v[44:45], v[154:155]
	v_pk_mul_f32 v[156:157], v[40:41], v[156:157]
	v_pk_mul_f32 v[160:161], v[46:47], v[160:161]
	v_pk_mul_f32 v[162:163], v[42:43], v[162:163]
	v_lshl_add_u64 v[158:159], s[42:43], 0, v[158:159]
	v_cvt_pk_bf16_f32 v154, v154, v155
	v_cvt_pk_bf16_f32 v155, v160, v161
	v_cvt_pk_bf16_f32 v156, v156, v157
	v_cvt_pk_bf16_f32 v157, v162, v163
	v_lshl_add_u64 v[158:159], v[158:159], 0, v[148:149]
	global_store_dwordx4 v[158:159], v[154:157], off sc1
	s_waitcnt vmcnt(7)
	v_lshlrev_b32_e32 v160, 16, v175
	v_and_b32_e32 v161, 0xffff0000, v175
	v_lshlrev_b32_e32 v154, 16, v174
	v_and_b32_e32 v155, 0xffff0000, v174
	v_lshlrev_b32_e32 v156, 16, v176
	v_and_b32_e32 v157, 0xffff0000, v176
	v_lshlrev_b32_e32 v162, 16, v177
	v_and_b32_e32 v163, 0xffff0000, v177
	v_pk_mul_f32 v[154:155], v[12:13], v[154:155]
	v_pk_mul_f32 v[156:157], v[8:9], v[156:157]
	v_pk_mul_f32 v[160:161], v[14:15], v[160:161]
	v_pk_mul_f32 v[162:163], v[10:11], v[162:163]
	v_cvt_pk_bf16_f32 v154, v154, v155
	v_cvt_pk_bf16_f32 v155, v160, v161
	v_cvt_pk_bf16_f32 v156, v156, v157
	v_cvt_pk_bf16_f32 v157, v162, v163
	global_store_dwordx4 v[158:159], v[154:157], off offset:256 sc1
	s_waitcnt vmcnt(7)
	v_lshlrev_b32_e32 v158, 16, v179
	v_and_b32_e32 v159, 0xffff0000, v179
	v_lshlrev_b32_e32 v154, 16, v178
	v_and_b32_e32 v155, 0xffff0000, v178
	v_lshlrev_b32_e32 v156, 16, v180
	v_and_b32_e32 v157, 0xffff0000, v180
	v_lshlrev_b32_e32 v160, 16, v181
	v_and_b32_e32 v161, 0xffff0000, v181
	v_pk_mul_f32 v[154:155], v[36:37], v[154:155]
	v_pk_mul_f32 v[156:157], v[32:33], v[156:157]
	v_pk_mul_f32 v[158:159], v[38:39], v[158:159]
	v_pk_mul_f32 v[160:161], v[34:35], v[160:161]
	v_cvt_pk_bf16_f32 v154, v154, v155
	v_cvt_pk_bf16_f32 v155, v158, v159
	v_cvt_pk_bf16_f32 v156, v156, v157
	v_cvt_pk_bf16_f32 v157, v160, v161
	v_lshl_add_u64 v[158:159], v[150:151], 0, v[148:149]
	global_store_dwordx4 v[158:159], v[154:157], off sc1
	s_waitcnt vmcnt(7)
	v_lshlrev_b32_e32 v148, 16, v182
	v_and_b32_e32 v149, 0xffff0000, v182
	v_lshlrev_b32_e32 v150, 16, v184
	v_and_b32_e32 v151, 0xffff0000, v184
	v_lshlrev_b32_e32 v154, 16, v183
	v_and_b32_e32 v155, 0xffff0000, v183
	v_lshlrev_b32_e32 v156, 16, v185
	v_and_b32_e32 v157, 0xffff0000, v185
	v_pk_mul_f32 v[148:149], v[4:5], v[148:149]
	v_pk_mul_f32 v[150:151], v[0:1], v[150:151]
	v_pk_mul_f32 v[154:155], v[6:7], v[154:155]
	v_pk_mul_f32 v[156:157], v[2:3], v[156:157]
	v_cvt_pk_bf16_f32 v148, v148, v149
	v_cvt_pk_bf16_f32 v149, v154, v155
	v_cvt_pk_bf16_f32 v150, v150, v151
	v_cvt_pk_bf16_f32 v151, v156, v157
	global_store_dwordx4 v[158:159], v[148:151], off offset:256 sc1
	s_cbranch_execnz .LBB0_995

.LBB0_1076:
	v_mov_b32_e32 v90, v192
	s_lshl_b32 s31, s10, 8
	s_or_b32 s31, s31, s57
	v_bfe_u32 v146, v90, 4, 2
	v_lshl_or_b32 v170, v146, 3, s31
	s_lshl_b32 s31, s40, 8
	s_add_i32 s31, s31, s56
	v_ashrrev_i32_e32 v171, 31, v170
	v_lshlrev_b64 v[144:145], 2, v[170:171]
	v_and_or_b32 v188, v90, 15, s31
	v_readlane_b32 s64, v254, 2
	v_lshl_add_u64 v[84:85], s[26:27], 0, v[144:145]
	v_lshl_add_u64 v[88:89], s[28:29], 0, v[144:145]
	v_ashrrev_i32_e32 v189, 31, v188
	v_readlane_b32 s65, v254, 3
	v_readlane_b32 s66, v254, 4
	v_readlane_b32 s67, v254, 5
	v_readlane_b32 s68, v254, 6
	v_readlane_b32 s69, v254, 7
	v_readlane_b32 s70, v254, 8
	v_readlane_b32 s71, v254, 9
	v_readlane_b32 s72, v254, 10
	v_readlane_b32 s73, v254, 11
	v_readlane_b32 s74, v254, 12
	v_readlane_b32 s75, v254, 13
	v_readlane_b32 s76, v254, 14
	v_readlane_b32 s77, v254, 15
	v_readlane_b32 s78, v254, 16
	v_readlane_b32 s79, v254, 17
	global_load_dwordx4 v[80:83], v[84:85], off offset:16
	s_nop 0
	global_load_dwordx4 v[84:87], v[84:85], off
	s_nop 0
	global_load_dwordx4 v[172:175], v[88:89], off offset:16
	global_load_dwordx4 v[176:179], v[88:89], off
	v_lshlrev_b64 v[88:89], 13, v[188:189]
	s_mov_b64 s[44:45], s[64:65]
	v_readlane_b32 s64, v254, 18
	v_or_b32_e32 v92, 0x80, v170
	v_lshl_add_u64 v[88:89], s[44:45], 0, v[88:89]
	v_readlane_b32 s78, v254, 32
	v_readlane_b32 s79, v254, 33
	v_ashrrev_i32_e32 v93, 31, v92
	v_lshl_add_u64 v[88:89], v[88:89], 0, v[144:145]
	v_lshl_add_u64 v[90:91], s[78:79], 0, v[144:145]
	v_lshlrev_b64 v[92:93], 2, v[92:93]
	global_load_dwordx4 v[180:183], v[88:89], off offset:16
	global_load_dwordx4 v[184:187], v[88:89], off
	global_load_dwordx4 v[204:207], v[90:91], off offset:16
	global_load_dwordx4 v[208:211], v[90:91], off
	v_lshl_add_u64 v[94:95], s[28:29], 0, v[92:93]
	global_load_dwordx4 v[212:215], v[94:95], off
	global_load_dwordx4 v[216:219], v[94:95], off offset:16
	global_load_dwordx4 v[220:223], v[90:91], off offset:512
	global_load_dwordx4 v[224:227], v[90:91], off offset:528
	v_lshl_add_u64 v[90:91], s[26:27], 0, v[92:93]
	global_load_dwordx4 v[92:95], v[90:91], off
	v_or_b32_e32 v90, 0x84, v170
	v_ashrrev_i32_e32 v91, 31, v90
	global_load_dwordx4 v[228:231], v[88:89], off offset:528
	global_load_dwordx4 v[232:235], v[88:89], off offset:512
	v_lshl_add_u64 v[88:89], v[90:91], 2, s[26:27]
	global_load_dwordx4 v[88:91], v[88:89], off
	v_and_b32_e32 v148, 64, v200
	v_xor_b32_e32 v147, 16, v200
	v_add_u32_e32 v148, 64, v148
	v_xor_b32_e32 v149, 32, v200
	v_cmp_lt_i32_e32 vcc, v147, v148
	v_or_b32_e32 v190, 16, v188
	v_ashrrev_i32_e32 v191, 31, v190
	v_cndmask_b32_e32 v147, v200, v147, vcc
	v_cmp_lt_i32_e32 vcc, v149, v148
	v_lshlrev_b32_e32 v202, 2, v147
	v_readlane_b32 s65, v254, 19
	v_cndmask_b32_e32 v148, v200, v149, vcc
	v_cmp_eq_u32_e32 vcc, 0, v146
	v_lshlrev_b64 v[146:147], 13, v[190:191]
	v_lshl_add_u64 v[146:147], s[44:45], 0, v[146:147]
	v_lshlrev_b32_e32 v201, 2, v148
	v_lshl_add_u64 v[148:149], v[146:147], 0, v[144:145]
	global_load_dwordx4 v[152:155], v[148:149], off offset:16 nt
	global_load_dwordx4 v[156:159], v[148:149], off nt
	global_load_dwordx4 v[144:147], v[148:149], off offset:528 nt
	s_nop 0
	global_load_dwordx4 v[148:151], v[148:149], off offset:512 nt
	v_readlane_b32 s66, v254, 20
	v_readlane_b32 s67, v254, 21
	v_lshlrev_b64 v[194:195], 11, v[188:189]
	v_readlane_b32 s64, v254, 56
	v_lshl_add_u64 v[194:195], v[194:195], 0, v[170:171]
	v_readlane_b32 s65, v254, 57
	s_lshl_b32 s40, s10, 2
	s_ashr_i32 s41, s40, 31
	v_lshl_add_u64 v[236:237], v[194:195], 2, s[64:65]
	v_lshlrev_b64 v[194:195], 1, v[194:195]
	v_readlane_b32 s68, v254, 22
	v_readlane_b32 s69, v254, 23
	v_readlane_b32 s70, v254, 24
	v_readlane_b32 s71, v254, 25
	v_readlane_b32 s72, v254, 26
	v_readlane_b32 s73, v254, 27
	v_readlane_b32 s74, v254, 28
	v_readlane_b32 s75, v254, 29
	v_readlane_b32 s76, v254, 30
	v_readlane_b32 s77, v254, 31
	v_readlane_b32 s66, v254, 58
	v_readlane_b32 s67, v254, 59
	s_waitcnt vmcnt(0)
	v_pk_add_f32 v[174:175], v[174:175], 1.0 op_sel_hi:[1,0]
	v_pk_add_f32 v[176:177], v[176:177], 1.0 op_sel_hi:[1,0]
	v_pk_add_f32 v[172:173], v[172:173], 1.0 op_sel_hi:[1,0]
	v_pk_add_f32 v[178:179], v[178:179], 1.0 op_sel_hi:[1,0]
	v_pk_fma_f32 v[138:139], v[138:139], v[82:83], v[182:183]
	v_pk_fma_f32 v[142:143], v[142:143], v[86:87], v[186:187]
	v_pk_fma_f32 v[140:141], v[140:141], v[84:85], v[184:185]
	v_pk_fma_f32 v[136:137], v[136:137], v[80:81], v[180:181]
	v_pk_mul_f32 v[186:187], v[208:209], v[176:177]
	v_pk_mul_f32 v[180:181], v[206:207], v[174:175]
	v_pk_mul_f32 v[182:183], v[204:205], v[172:173]
	v_pk_add_f32 v[174:175], v[212:213], 1.0 op_sel_hi:[1,0]
	v_pk_add_f32 v[204:205], v[218:219], 1.0 op_sel_hi:[1,0]
	v_pk_mul_f32 v[184:185], v[210:211], v[178:179]
	global_store_dwordx4 v[236:237], v[140:143], off
	global_store_dwordx4 v[236:237], v[136:139], off offset:16 nt
	v_pk_mul_f32 v[178:179], v[220:221], v[174:175]
	v_pk_mul_f32 v[174:175], v[226:227], v[204:205]
	v_pk_mul_f32 v[204:205], v[186:187], v[140:141]
	v_mul_f32_e32 v141, v141, v141
	v_fmac_f32_e32 v141, v140, v140
	v_mul_f32_e32 v140, v143, v143
	v_pk_add_f32 v[172:173], v[214:215], 1.0 op_sel_hi:[1,0]
	v_pk_add_f32 v[206:207], v[216:217], 1.0 op_sel_hi:[1,0]
	v_pk_mul_f32 v[210:211], v[182:183], v[136:137]
	v_fmac_f32_e32 v140, v142, v142
	v_mul_f32_e32 v137, v137, v137
	v_pk_mul_f32 v[176:177], v[222:223], v[172:173]
	v_pk_mul_f32 v[172:173], v[224:225], v[206:207]
	v_pk_mul_f32 v[206:207], v[184:185], v[142:143]
	v_pk_mul_f32 v[208:209], v[180:181], v[138:139]
	v_add_f32_e32 v140, v141, v140
	v_fmac_f32_e32 v137, v136, v136
	v_cvt_pk_bf16_f32 v204, v204, v205
	v_cvt_pk_bf16_f32 v205, v206, v207
	v_cvt_pk_bf16_f32 v206, v210, v211
	v_cvt_pk_bf16_f32 v207, v208, v209
	v_lshl_add_u64 v[208:209], s[86:87], 0, v[194:195]
	v_add_f32_e32 v136, v140, v137
	v_mul_f32_e32 v137, v139, v139
	v_pk_fma_f32 v[134:135], v[134:135], v[94:95], v[234:235]
	v_pk_fma_f32 v[132:133], v[132:133], v[92:93], v[232:233]
	global_store_dwordx4 v[208:209], v[204:207], off sc1
	v_fmac_f32_e32 v137, v138, v138
	v_pk_fma_f32 v[130:131], v[130:131], v[90:91], v[230:231]
	v_pk_fma_f32 v[128:129], v[128:129], v[88:89], v[228:229]
	global_store_dwordx4 v[236:237], v[132:135], off offset:512 nt
	global_store_dwordx4 v[236:237], v[128:131], off offset:528 nt
	v_pk_mul_f32 v[138:139], v[178:179], v[132:133]
	v_mul_f32_e32 v133, v133, v133
	v_fmac_f32_e32 v133, v132, v132
	v_mul_f32_e32 v132, v135, v135
	v_fmac_f32_e32 v132, v134, v134
	v_add_f32_e32 v132, v133, v132
	v_mul_f32_e32 v133, v129, v129
	v_pk_mul_f32 v[140:141], v[174:175], v[130:131]
	v_fmac_f32_e32 v133, v128, v128
	v_mul_f32_e32 v131, v131, v131
	v_add_f32_e32 v132, v132, v133
	v_fmac_f32_e32 v131, v130, v130
	v_add_f32_e32 v142, v137, v136
	v_add_f32_e32 v130, v131, v132
	v_add_f32_e32 v133, v142, v130
	v_pk_mul_f32 v[136:137], v[176:177], v[134:135]
	ds_bpermute_b32 v134, v202, v133
	v_pk_mul_f32 v[128:129], v[172:173], v[128:129]
	v_or_b32_e32 v194, 0x100, v194
	v_cvt_pk_bf16_f32 v132, v128, v129
	v_cvt_pk_bf16_f32 v130, v138, v139
	s_waitcnt lgkmcnt(0)
	v_add_f32_e32 v128, v133, v134
	ds_bpermute_b32 v129, v201, v128
	v_cvt_pk_bf16_f32 v131, v136, v137
	v_cvt_pk_bf16_f32 v133, v140, v141
	v_lshl_add_u64 v[134:135], s[86:87], 0, v[194:195]
	global_store_dwordx4 v[134:135], v[130:133], off sc1
	s_and_saveexec_b64 s[42:43], vcc
	s_cbranch_execz .LBB0_1078
	v_lshlrev_b64 v[130:131], 7, v[188:189]
	v_lshl_add_u64 v[130:131], s[14:15], 0, v[130:131]
	v_lshl_add_u64 v[130:131], s[40:41], 2, v[130:131]
	s_lshl_b32 s10, s55, 2
	v_lshl_add_u64 v[130:131], v[130:131], 0, s[10:11]
	s_waitcnt lgkmcnt(0)
	v_add_f32_e32 v128, v128, v129
	global_store_dword v[130:131], v128, off
.LBB0_1078:
	s_or_b64 exec, exec, s[42:43]
	v_or_b32_e32 v194, 32, v188
	v_ashrrev_i32_e32 v195, 31, v194
	v_readlane_b32 s64, v254, 2
	s_waitcnt lgkmcnt(0)
	v_lshlrev_b64 v[128:129], 13, v[194:195]
	v_readlane_b32 s65, v254, 3
	v_readlane_b32 s66, v254, 4
	v_readlane_b32 s67, v254, 5
	v_lshl_add_u64 v[128:129], s[64:65], 0, v[128:129]
	v_lshl_add_u64 v[132:133], v[170:171], 2, v[128:129]
	global_load_dwordx4 v[136:139], v[132:133], off offset:16 nt
	global_load_dwordx4 v[140:143], v[132:133], off nt
	global_load_dwordx4 v[128:131], v[132:133], off offset:528 nt
	s_nop 0
	global_load_dwordx4 v[132:135], v[132:133], off offset:512 nt
	v_lshlrev_b64 v[204:205], 11, v[190:191]
	v_readlane_b32 s64, v254, 56
	v_lshl_add_u64 v[204:205], v[204:205], 0, v[170:171]
	v_readlane_b32 s65, v254, 57
	v_pk_fma_f32 v[126:127], v[126:127], v[86:87], v[158:159]
	v_pk_fma_f32 v[124:125], v[124:125], v[84:85], v[156:157]
	v_lshl_add_u64 v[156:157], v[204:205], 2, s[64:65]
	v_pk_fma_f32 v[122:123], v[122:123], v[82:83], v[154:155]
	v_pk_fma_f32 v[120:121], v[120:121], v[80:81], v[152:153]
	global_store_dwordx4 v[156:157], v[124:127], off
	global_store_dwordx4 v[156:157], v[120:123], off offset:16 nt
	v_pk_mul_f32 v[152:153], v[186:187], v[124:125]
	v_mul_f32_e32 v125, v125, v125
	v_fmac_f32_e32 v125, v124, v124
	v_mul_f32_e32 v124, v127, v127
	v_pk_mul_f32 v[154:155], v[184:185], v[126:127]
	v_pk_mul_f32 v[158:159], v[180:181], v[122:123]
	v_pk_mul_f32 v[206:207], v[182:183], v[120:121]
	v_fmac_f32_e32 v124, v126, v126
	v_mul_f32_e32 v121, v121, v121
	v_cvt_pk_bf16_f32 v152, v152, v153
	v_cvt_pk_bf16_f32 v153, v154, v155
	v_cvt_pk_bf16_f32 v155, v158, v159
	v_lshlrev_b64 v[158:159], 1, v[204:205]
	v_add_f32_e32 v124, v125, v124
	v_fmac_f32_e32 v121, v120, v120
	v_cvt_pk_bf16_f32 v154, v206, v207
	v_lshl_add_u64 v[204:205], s[86:87], 0, v[158:159]
	v_add_f32_e32 v120, v124, v121
	v_mul_f32_e32 v121, v123, v123
	v_pk_fma_f32 v[118:119], v[118:119], v[94:95], v[150:151]
	v_pk_fma_f32 v[116:117], v[116:117], v[92:93], v[148:149]
	global_store_dwordx4 v[204:205], v[152:155], off sc1
	v_fmac_f32_e32 v121, v122, v122
	v_pk_fma_f32 v[114:115], v[114:115], v[90:91], v[146:147]
	v_pk_fma_f32 v[112:113], v[112:113], v[88:89], v[144:145]
	global_store_dwordx4 v[156:157], v[116:119], off offset:512 nt
	global_store_dwordx4 v[156:157], v[112:115], off offset:528 nt
	v_pk_mul_f32 v[122:123], v[178:179], v[116:117]
	v_mul_f32_e32 v117, v117, v117
	v_fmac_f32_e32 v117, v116, v116
	v_mul_f32_e32 v116, v119, v119
	v_fmac_f32_e32 v116, v118, v118
	v_add_f32_e32 v116, v117, v116
	v_mul_f32_e32 v117, v113, v113
	v_pk_mul_f32 v[124:125], v[174:175], v[114:115]
	v_fmac_f32_e32 v117, v112, v112
	v_mul_f32_e32 v115, v115, v115
	v_add_f32_e32 v116, v116, v117
	v_fmac_f32_e32 v115, v114, v114
	v_add_f32_e32 v126, v121, v120
	v_add_f32_e32 v114, v115, v116
	v_add_f32_e32 v117, v126, v114
	v_pk_mul_f32 v[120:121], v[176:177], v[118:119]
	ds_bpermute_b32 v118, v202, v117
	v_pk_mul_f32 v[112:113], v[172:173], v[112:113]
	v_or_b32_e32 v158, 0x100, v158
	v_cvt_pk_bf16_f32 v116, v112, v113
	v_cvt_pk_bf16_f32 v114, v122, v123
	s_waitcnt lgkmcnt(0)
	v_add_f32_e32 v112, v117, v118
	ds_bpermute_b32 v113, v201, v112
	v_cvt_pk_bf16_f32 v115, v120, v121
	v_cvt_pk_bf16_f32 v117, v124, v125
	v_lshl_add_u64 v[118:119], s[86:87], 0, v[158:159]
	v_readlane_b32 s68, v254, 6
	v_readlane_b32 s69, v254, 7
	v_readlane_b32 s70, v254, 8
	v_readlane_b32 s71, v254, 9
	v_readlane_b32 s72, v254, 10
	v_readlane_b32 s73, v254, 11
	v_readlane_b32 s74, v254, 12
	v_readlane_b32 s75, v254, 13
	v_readlane_b32 s76, v254, 14
	v_readlane_b32 s77, v254, 15
	v_readlane_b32 s78, v254, 16
	v_readlane_b32 s79, v254, 17
	v_readlane_b32 s66, v254, 58
	v_readlane_b32 s67, v254, 59
	global_store_dwordx4 v[118:119], v[114:117], off sc1
	s_and_saveexec_b64 s[42:43], vcc
	s_cbranch_execz .LBB0_1080
	v_lshlrev_b64 v[114:115], 7, v[190:191]
	v_lshl_add_u64 v[114:115], s[14:15], 0, v[114:115]
	v_lshl_add_u64 v[114:115], s[40:41], 2, v[114:115]
	s_lshl_b32 s10, s55, 2
	v_lshl_add_u64 v[114:115], v[114:115], 0, s[10:11]
	s_waitcnt lgkmcnt(0)
	v_add_f32_e32 v112, v112, v113
	global_store_dword v[114:115], v112, off
.LBB0_1080:
	s_or_b64 exec, exec, s[42:43]
	v_or_b32_e32 v144, 48, v188
	v_ashrrev_i32_e32 v145, 31, v144
	v_readlane_b32 s64, v254, 2
	s_waitcnt lgkmcnt(0)
	v_lshlrev_b64 v[112:113], 13, v[144:145]
	v_readlane_b32 s65, v254, 3
	v_readlane_b32 s66, v254, 4
	v_readlane_b32 s67, v254, 5
	v_lshl_add_u64 v[112:113], s[64:65], 0, v[112:113]
	v_lshl_add_u64 v[116:117], v[170:171], 2, v[112:113]
	global_load_dwordx4 v[120:123], v[116:117], off offset:16 nt
	global_load_dwordx4 v[124:127], v[116:117], off nt
	global_load_dwordx4 v[112:115], v[116:117], off offset:528 nt
	s_nop 0
	global_load_dwordx4 v[116:119], v[116:117], off offset:512 nt
	v_lshlrev_b64 v[146:147], 11, v[194:195]
	v_readlane_b32 s64, v254, 56
	v_lshl_add_u64 v[146:147], v[146:147], 0, v[170:171]
	v_readlane_b32 s65, v254, 57
	s_waitcnt vmcnt(12)
	v_pk_fma_f32 v[110:111], v[110:111], v[86:87], v[142:143]
	v_pk_fma_f32 v[108:109], v[108:109], v[84:85], v[140:141]
	v_lshl_add_u64 v[140:141], v[146:147], 2, s[64:65]
	v_pk_fma_f32 v[106:107], v[106:107], v[82:83], v[138:139]
	v_pk_fma_f32 v[104:105], v[104:105], v[80:81], v[136:137]
	global_store_dwordx4 v[140:141], v[108:111], off
	global_store_dwordx4 v[140:141], v[104:107], off offset:16 nt
	v_pk_mul_f32 v[136:137], v[186:187], v[108:109]
	v_mul_f32_e32 v109, v109, v109
	v_fmac_f32_e32 v109, v108, v108
	v_mul_f32_e32 v108, v111, v111
	v_pk_mul_f32 v[138:139], v[184:185], v[110:111]
	v_pk_mul_f32 v[142:143], v[180:181], v[106:107]
	v_pk_mul_f32 v[148:149], v[182:183], v[104:105]
	v_fmac_f32_e32 v108, v110, v110
	v_mul_f32_e32 v105, v105, v105
	v_cvt_pk_bf16_f32 v136, v136, v137
	v_cvt_pk_bf16_f32 v137, v138, v139
	v_cvt_pk_bf16_f32 v139, v142, v143
	v_lshlrev_b64 v[142:143], 1, v[146:147]
	v_add_f32_e32 v108, v109, v108
	v_fmac_f32_e32 v105, v104, v104
	v_cvt_pk_bf16_f32 v138, v148, v149
	v_lshl_add_u64 v[146:147], s[86:87], 0, v[142:143]
	v_add_f32_e32 v104, v108, v105
	v_mul_f32_e32 v105, v107, v107
	s_waitcnt vmcnt(12)
	v_pk_fma_f32 v[102:103], v[102:103], v[94:95], v[134:135]
	v_pk_fma_f32 v[100:101], v[100:101], v[92:93], v[132:133]
	global_store_dwordx4 v[146:147], v[136:139], off sc1
	v_fmac_f32_e32 v105, v106, v106
	v_pk_fma_f32 v[98:99], v[98:99], v[90:91], v[130:131]
	v_pk_fma_f32 v[96:97], v[96:97], v[88:89], v[128:129]
	global_store_dwordx4 v[140:141], v[100:103], off offset:512 nt
	global_store_dwordx4 v[140:141], v[96:99], off offset:528 nt
	v_pk_mul_f32 v[106:107], v[178:179], v[100:101]
	v_mul_f32_e32 v101, v101, v101
	v_fmac_f32_e32 v101, v100, v100
	v_mul_f32_e32 v100, v103, v103
	v_fmac_f32_e32 v100, v102, v102
	v_add_f32_e32 v100, v101, v100
	v_mul_f32_e32 v101, v97, v97
	v_pk_mul_f32 v[108:109], v[174:175], v[98:99]
	v_fmac_f32_e32 v101, v96, v96
	v_mul_f32_e32 v99, v99, v99
	v_add_f32_e32 v100, v100, v101
	v_fmac_f32_e32 v99, v98, v98
	v_add_f32_e32 v110, v105, v104
	v_add_f32_e32 v98, v99, v100
	v_add_f32_e32 v101, v110, v98
	v_pk_mul_f32 v[104:105], v[176:177], v[102:103]
	ds_bpermute_b32 v102, v202, v101
	v_pk_mul_f32 v[96:97], v[172:173], v[96:97]
	v_or_b32_e32 v142, 0x100, v142
	v_cvt_pk_bf16_f32 v100, v96, v97
	v_cvt_pk_bf16_f32 v98, v106, v107
	s_waitcnt lgkmcnt(0)
	v_add_f32_e32 v96, v101, v102
	ds_bpermute_b32 v97, v201, v96
	v_cvt_pk_bf16_f32 v99, v104, v105
	v_cvt_pk_bf16_f32 v101, v108, v109
	v_lshl_add_u64 v[102:103], s[86:87], 0, v[142:143]
	v_readlane_b32 s68, v254, 6
	v_readlane_b32 s69, v254, 7
	v_readlane_b32 s70, v254, 8
	v_readlane_b32 s71, v254, 9
	v_readlane_b32 s72, v254, 10
	v_readlane_b32 s73, v254, 11
	v_readlane_b32 s74, v254, 12
	v_readlane_b32 s75, v254, 13
	v_readlane_b32 s76, v254, 14
	v_readlane_b32 s77, v254, 15
	v_readlane_b32 s78, v254, 16
	v_readlane_b32 s79, v254, 17
	v_readlane_b32 s66, v254, 58
	v_readlane_b32 s67, v254, 59
	global_store_dwordx4 v[102:103], v[98:101], off sc1
	s_and_saveexec_b64 s[42:43], vcc
	s_cbranch_execz .LBB0_1082
	v_lshlrev_b64 v[98:99], 7, v[194:195]
	v_lshl_add_u64 v[98:99], s[14:15], 0, v[98:99]
	v_lshl_add_u64 v[98:99], s[40:41], 2, v[98:99]
	s_lshl_b32 s10, s55, 2
	v_lshl_add_u64 v[98:99], v[98:99], 0, s[10:11]
	s_waitcnt lgkmcnt(0)
	v_add_f32_e32 v96, v96, v97
	global_store_dword v[98:99], v96, off
.LBB0_1082:
	s_or_b64 exec, exec, s[42:43]
	v_add_u32_e32 v128, 0x80, v188
	v_ashrrev_i32_e32 v129, 31, v128
	v_readlane_b32 s64, v254, 2
	s_waitcnt lgkmcnt(0)
	v_lshlrev_b64 v[96:97], 13, v[128:129]
	v_readlane_b32 s65, v254, 3
	v_readlane_b32 s66, v254, 4
	v_readlane_b32 s67, v254, 5
	v_lshl_add_u64 v[96:97], s[64:65], 0, v[96:97]
	v_lshl_add_u64 v[100:101], v[170:171], 2, v[96:97]
	global_load_dwordx4 v[104:107], v[100:101], off offset:16 nt
	global_load_dwordx4 v[108:111], v[100:101], off nt
	global_load_dwordx4 v[96:99], v[100:101], off offset:528 nt
	s_nop 0
	global_load_dwordx4 v[100:103], v[100:101], off offset:512 nt
	v_lshlrev_b64 v[130:131], 11, v[144:145]
	v_readlane_b32 s64, v254, 56
	v_lshl_add_u64 v[130:131], v[130:131], 0, v[170:171]
	v_readlane_b32 s65, v254, 57
	s_waitcnt vmcnt(12)
	v_pk_fma_f32 v[78:79], v[78:79], v[86:87], v[126:127]
	v_pk_fma_f32 v[76:77], v[76:77], v[84:85], v[124:125]
	v_lshl_add_u64 v[124:125], v[130:131], 2, s[64:65]
	v_pk_fma_f32 v[74:75], v[74:75], v[82:83], v[122:123]
	v_pk_fma_f32 v[72:73], v[72:73], v[80:81], v[120:121]
	global_store_dwordx4 v[124:125], v[76:79], off
	global_store_dwordx4 v[124:125], v[72:75], off offset:16 nt
	v_pk_mul_f32 v[120:121], v[186:187], v[76:77]
	v_mul_f32_e32 v77, v77, v77
	v_fmac_f32_e32 v77, v76, v76
	v_mul_f32_e32 v76, v79, v79
	v_pk_mul_f32 v[122:123], v[184:185], v[78:79]
	v_pk_mul_f32 v[126:127], v[180:181], v[74:75]
	v_pk_mul_f32 v[132:133], v[182:183], v[72:73]
	v_fmac_f32_e32 v76, v78, v78
	v_mul_f32_e32 v73, v73, v73
	v_cvt_pk_bf16_f32 v120, v120, v121
	v_cvt_pk_bf16_f32 v121, v122, v123
	v_cvt_pk_bf16_f32 v123, v126, v127
	v_lshlrev_b64 v[126:127], 1, v[130:131]
	v_add_f32_e32 v76, v77, v76
	v_fmac_f32_e32 v73, v72, v72
	v_cvt_pk_bf16_f32 v122, v132, v133
	v_lshl_add_u64 v[130:131], s[86:87], 0, v[126:127]
	v_add_f32_e32 v72, v76, v73
	v_mul_f32_e32 v73, v75, v75
	s_waitcnt vmcnt(12)
	v_pk_fma_f32 v[70:71], v[70:71], v[94:95], v[118:119]
	v_pk_fma_f32 v[68:69], v[68:69], v[92:93], v[116:117]
	global_store_dwordx4 v[130:131], v[120:123], off sc1
	v_fmac_f32_e32 v73, v74, v74
	v_pk_fma_f32 v[66:67], v[66:67], v[90:91], v[114:115]
	v_pk_fma_f32 v[64:65], v[64:65], v[88:89], v[112:113]
	global_store_dwordx4 v[124:125], v[68:71], off offset:512 nt
	global_store_dwordx4 v[124:125], v[64:67], off offset:528 nt
	v_pk_mul_f32 v[74:75], v[178:179], v[68:69]
	v_mul_f32_e32 v69, v69, v69
	v_fmac_f32_e32 v69, v68, v68
	v_mul_f32_e32 v68, v71, v71
	v_fmac_f32_e32 v68, v70, v70
	v_add_f32_e32 v68, v69, v68
	v_mul_f32_e32 v69, v65, v65
	v_pk_mul_f32 v[76:77], v[174:175], v[66:67]
	v_fmac_f32_e32 v69, v64, v64
	v_mul_f32_e32 v67, v67, v67
	v_add_f32_e32 v68, v68, v69
	v_fmac_f32_e32 v67, v66, v66
	v_add_f32_e32 v78, v73, v72
	v_add_f32_e32 v66, v67, v68
	v_add_f32_e32 v69, v78, v66
	v_pk_mul_f32 v[72:73], v[176:177], v[70:71]
	ds_bpermute_b32 v70, v202, v69
	v_pk_mul_f32 v[64:65], v[172:173], v[64:65]
	v_or_b32_e32 v126, 0x100, v126
	v_cvt_pk_bf16_f32 v68, v64, v65
	v_cvt_pk_bf16_f32 v66, v74, v75
	s_waitcnt lgkmcnt(0)
	v_add_f32_e32 v64, v69, v70
	ds_bpermute_b32 v65, v201, v64
	v_cvt_pk_bf16_f32 v67, v72, v73
	v_cvt_pk_bf16_f32 v69, v76, v77
	v_lshl_add_u64 v[70:71], s[86:87], 0, v[126:127]
	v_readlane_b32 s68, v254, 6
	v_readlane_b32 s69, v254, 7
	v_readlane_b32 s70, v254, 8
	v_readlane_b32 s71, v254, 9
	v_readlane_b32 s72, v254, 10
	v_readlane_b32 s73, v254, 11
	v_readlane_b32 s74, v254, 12
	v_readlane_b32 s75, v254, 13
	v_readlane_b32 s76, v254, 14
	v_readlane_b32 s77, v254, 15
	v_readlane_b32 s78, v254, 16
	v_readlane_b32 s79, v254, 17
	v_readlane_b32 s66, v254, 58
	v_readlane_b32 s67, v254, 59
	global_store_dwordx4 v[70:71], v[66:69], off sc1
	s_and_saveexec_b64 s[42:43], vcc
	s_cbranch_execz .LBB0_1084
	v_lshlrev_b64 v[66:67], 7, v[144:145]
	v_lshl_add_u64 v[66:67], s[14:15], 0, v[66:67]
	v_lshl_add_u64 v[66:67], s[40:41], 2, v[66:67]
	s_lshl_b32 s10, s55, 2
	v_lshl_add_u64 v[66:67], v[66:67], 0, s[10:11]
	s_waitcnt lgkmcnt(0)
	v_add_f32_e32 v64, v64, v65
	global_store_dword v[66:67], v64, off
.LBB0_1084:
	s_or_b64 exec, exec, s[42:43]
	v_or_b32_e32 v112, 16, v128
	v_ashrrev_i32_e32 v113, 31, v112
	v_readlane_b32 s64, v254, 2
	s_waitcnt lgkmcnt(0)
	v_lshlrev_b64 v[64:65], 13, v[112:113]
	v_readlane_b32 s65, v254, 3
	v_readlane_b32 s66, v254, 4
	v_readlane_b32 s67, v254, 5
	v_lshl_add_u64 v[64:65], s[64:65], 0, v[64:65]
	v_lshl_add_u64 v[68:69], v[170:171], 2, v[64:65]
	global_load_dwordx4 v[72:75], v[68:69], off offset:16 nt
	global_load_dwordx4 v[76:79], v[68:69], off nt
	global_load_dwordx4 v[64:67], v[68:69], off offset:528 nt
	s_nop 0
	global_load_dwordx4 v[68:71], v[68:69], off offset:512 nt
	v_lshlrev_b64 v[114:115], 11, v[128:129]
	v_readlane_b32 s64, v254, 56
	v_lshl_add_u64 v[114:115], v[114:115], 0, v[170:171]
	v_readlane_b32 s65, v254, 57
	s_waitcnt vmcnt(12)
	v_pk_fma_f32 v[62:63], v[62:63], v[86:87], v[110:111]
	v_pk_fma_f32 v[60:61], v[60:61], v[84:85], v[108:109]
	v_lshl_add_u64 v[108:109], v[114:115], 2, s[64:65]
	v_pk_fma_f32 v[58:59], v[58:59], v[82:83], v[106:107]
	v_pk_fma_f32 v[56:57], v[56:57], v[80:81], v[104:105]
	global_store_dwordx4 v[108:109], v[60:63], off
	global_store_dwordx4 v[108:109], v[56:59], off offset:16 nt
	v_pk_mul_f32 v[104:105], v[186:187], v[60:61]
	v_mul_f32_e32 v61, v61, v61
	v_fmac_f32_e32 v61, v60, v60
	v_mul_f32_e32 v60, v63, v63
	v_pk_mul_f32 v[106:107], v[184:185], v[62:63]
	v_pk_mul_f32 v[110:111], v[180:181], v[58:59]
	v_pk_mul_f32 v[116:117], v[182:183], v[56:57]
	v_fmac_f32_e32 v60, v62, v62
	v_mul_f32_e32 v57, v57, v57
	v_cvt_pk_bf16_f32 v104, v104, v105
	v_cvt_pk_bf16_f32 v105, v106, v107
	v_cvt_pk_bf16_f32 v107, v110, v111
	v_lshlrev_b64 v[110:111], 1, v[114:115]
	v_add_f32_e32 v60, v61, v60
	v_fmac_f32_e32 v57, v56, v56
	v_cvt_pk_bf16_f32 v106, v116, v117
	v_lshl_add_u64 v[114:115], s[86:87], 0, v[110:111]
	v_add_f32_e32 v56, v60, v57
	v_mul_f32_e32 v57, v59, v59
	s_waitcnt vmcnt(12)
	v_pk_fma_f32 v[54:55], v[54:55], v[94:95], v[102:103]
	v_pk_fma_f32 v[52:53], v[52:53], v[92:93], v[100:101]
	global_store_dwordx4 v[114:115], v[104:107], off sc1
	v_fmac_f32_e32 v57, v58, v58
	v_pk_fma_f32 v[50:51], v[50:51], v[90:91], v[98:99]
	v_pk_fma_f32 v[48:49], v[48:49], v[88:89], v[96:97]
	global_store_dwordx4 v[108:109], v[52:55], off offset:512 nt
	global_store_dwordx4 v[108:109], v[48:51], off offset:528 nt
	v_pk_mul_f32 v[58:59], v[178:179], v[52:53]
	v_mul_f32_e32 v53, v53, v53
	v_fmac_f32_e32 v53, v52, v52
	v_mul_f32_e32 v52, v55, v55
	v_fmac_f32_e32 v52, v54, v54
	v_add_f32_e32 v52, v53, v52
	v_mul_f32_e32 v53, v49, v49
	v_pk_mul_f32 v[60:61], v[174:175], v[50:51]
	v_fmac_f32_e32 v53, v48, v48
	v_mul_f32_e32 v51, v51, v51
	v_add_f32_e32 v52, v52, v53
	v_fmac_f32_e32 v51, v50, v50
	v_add_f32_e32 v62, v57, v56
	v_add_f32_e32 v50, v51, v52
	v_add_f32_e32 v53, v62, v50
	v_pk_mul_f32 v[56:57], v[176:177], v[54:55]
	ds_bpermute_b32 v54, v202, v53
	v_pk_mul_f32 v[48:49], v[172:173], v[48:49]
	v_or_b32_e32 v110, 0x100, v110
	v_cvt_pk_bf16_f32 v52, v48, v49
	v_cvt_pk_bf16_f32 v50, v58, v59
	s_waitcnt lgkmcnt(0)
	v_add_f32_e32 v48, v53, v54
	ds_bpermute_b32 v49, v201, v48
	v_cvt_pk_bf16_f32 v51, v56, v57
	v_cvt_pk_bf16_f32 v53, v60, v61
	v_lshl_add_u64 v[54:55], s[86:87], 0, v[110:111]
	v_readlane_b32 s68, v254, 6
	v_readlane_b32 s69, v254, 7
	v_readlane_b32 s70, v254, 8
	v_readlane_b32 s71, v254, 9
	v_readlane_b32 s72, v254, 10
	v_readlane_b32 s73, v254, 11
	v_readlane_b32 s74, v254, 12
	v_readlane_b32 s75, v254, 13
	v_readlane_b32 s76, v254, 14
	v_readlane_b32 s77, v254, 15
	v_readlane_b32 s78, v254, 16
	v_readlane_b32 s79, v254, 17
	v_readlane_b32 s66, v254, 58
	v_readlane_b32 s67, v254, 59
	global_store_dwordx4 v[54:55], v[50:53], off sc1
	s_and_saveexec_b64 s[42:43], vcc
	s_cbranch_execz .LBB0_1086
	v_lshlrev_b64 v[50:51], 7, v[128:129]
	v_lshl_add_u64 v[50:51], s[14:15], 0, v[50:51]
	v_lshl_add_u64 v[50:51], s[40:41], 2, v[50:51]
	s_lshl_b32 s10, s55, 2
	v_lshl_add_u64 v[50:51], v[50:51], 0, s[10:11]
	s_waitcnt lgkmcnt(0)
	v_add_f32_e32 v48, v48, v49
	global_store_dword v[50:51], v48, off
.LBB0_1086:
	s_or_b64 exec, exec, s[42:43]
	v_or_b32_e32 v96, 32, v128
	v_ashrrev_i32_e32 v97, 31, v96
	v_readlane_b32 s64, v254, 2
	s_waitcnt lgkmcnt(0)
	v_lshlrev_b64 v[48:49], 13, v[96:97]
	v_readlane_b32 s65, v254, 3
	v_readlane_b32 s66, v254, 4
	v_readlane_b32 s67, v254, 5
	v_lshl_add_u64 v[48:49], s[64:65], 0, v[48:49]
	v_lshl_add_u64 v[52:53], v[170:171], 2, v[48:49]
	global_load_dwordx4 v[56:59], v[52:53], off offset:16 nt
	global_load_dwordx4 v[60:63], v[52:53], off nt
	global_load_dwordx4 v[48:51], v[52:53], off offset:528 nt
	s_nop 0
	global_load_dwordx4 v[52:55], v[52:53], off offset:512 nt
	v_lshlrev_b64 v[98:99], 11, v[112:113]
	v_readlane_b32 s64, v254, 56
	v_lshl_add_u64 v[98:99], v[98:99], 0, v[170:171]
	v_readlane_b32 s65, v254, 57
	s_waitcnt vmcnt(12)
	v_pk_fma_f32 v[46:47], v[46:47], v[86:87], v[78:79]
	v_pk_fma_f32 v[44:45], v[44:45], v[84:85], v[76:77]
	v_lshl_add_u64 v[76:77], v[98:99], 2, s[64:65]
	v_pk_fma_f32 v[42:43], v[42:43], v[82:83], v[74:75]
	v_pk_fma_f32 v[40:41], v[40:41], v[80:81], v[72:73]
	global_store_dwordx4 v[76:77], v[44:47], off
	global_store_dwordx4 v[76:77], v[40:43], off offset:16 nt
	v_pk_mul_f32 v[72:73], v[186:187], v[44:45]
	v_mul_f32_e32 v45, v45, v45
	v_fmac_f32_e32 v45, v44, v44
	v_mul_f32_e32 v44, v47, v47
	v_pk_mul_f32 v[74:75], v[184:185], v[46:47]
	v_pk_mul_f32 v[78:79], v[180:181], v[42:43]
	v_pk_mul_f32 v[100:101], v[182:183], v[40:41]
	v_fmac_f32_e32 v44, v46, v46
	v_mul_f32_e32 v41, v41, v41
	v_cvt_pk_bf16_f32 v72, v72, v73
	v_cvt_pk_bf16_f32 v73, v74, v75
	v_cvt_pk_bf16_f32 v75, v78, v79
	v_lshlrev_b64 v[78:79], 1, v[98:99]
	v_add_f32_e32 v44, v45, v44
	v_fmac_f32_e32 v41, v40, v40
	v_cvt_pk_bf16_f32 v74, v100, v101
	v_lshl_add_u64 v[98:99], s[86:87], 0, v[78:79]
	v_add_f32_e32 v40, v44, v41
	v_mul_f32_e32 v41, v43, v43
	s_waitcnt vmcnt(12)
	v_pk_fma_f32 v[38:39], v[38:39], v[94:95], v[70:71]
	v_pk_fma_f32 v[36:37], v[36:37], v[92:93], v[68:69]
	global_store_dwordx4 v[98:99], v[72:75], off sc1
	v_fmac_f32_e32 v41, v42, v42
	v_pk_fma_f32 v[34:35], v[34:35], v[90:91], v[66:67]
	v_pk_fma_f32 v[32:33], v[32:33], v[88:89], v[64:65]
	global_store_dwordx4 v[76:77], v[36:39], off offset:512 nt
	global_store_dwordx4 v[76:77], v[32:35], off offset:528 nt
	v_pk_mul_f32 v[42:43], v[178:179], v[36:37]
	v_mul_f32_e32 v37, v37, v37
	v_fmac_f32_e32 v37, v36, v36
	v_mul_f32_e32 v36, v39, v39
	v_fmac_f32_e32 v36, v38, v38
	v_add_f32_e32 v36, v37, v36
	v_mul_f32_e32 v37, v33, v33
	v_pk_mul_f32 v[44:45], v[174:175], v[34:35]
	v_fmac_f32_e32 v37, v32, v32
	v_mul_f32_e32 v35, v35, v35
	v_add_f32_e32 v36, v36, v37
	v_fmac_f32_e32 v35, v34, v34
	v_add_f32_e32 v46, v41, v40
	v_add_f32_e32 v34, v35, v36
	v_add_f32_e32 v37, v46, v34
	v_pk_mul_f32 v[40:41], v[176:177], v[38:39]
	ds_bpermute_b32 v38, v202, v37
	v_pk_mul_f32 v[32:33], v[172:173], v[32:33]
	v_or_b32_e32 v78, 0x100, v78
	v_cvt_pk_bf16_f32 v36, v32, v33
	v_cvt_pk_bf16_f32 v34, v42, v43
	s_waitcnt lgkmcnt(0)
	v_add_f32_e32 v32, v37, v38
	ds_bpermute_b32 v33, v201, v32
	v_cvt_pk_bf16_f32 v35, v40, v41
	v_cvt_pk_bf16_f32 v37, v44, v45
	v_lshl_add_u64 v[38:39], s[86:87], 0, v[78:79]
	v_readlane_b32 s68, v254, 6
	v_readlane_b32 s69, v254, 7
	v_readlane_b32 s70, v254, 8
	v_readlane_b32 s71, v254, 9
	v_readlane_b32 s72, v254, 10
	v_readlane_b32 s73, v254, 11
	v_readlane_b32 s74, v254, 12
	v_readlane_b32 s75, v254, 13
	v_readlane_b32 s76, v254, 14
	v_readlane_b32 s77, v254, 15
	v_readlane_b32 s78, v254, 16
	v_readlane_b32 s79, v254, 17
	v_readlane_b32 s66, v254, 58
	v_readlane_b32 s67, v254, 59
	global_store_dwordx4 v[38:39], v[34:37], off sc1
	s_and_saveexec_b64 s[42:43], vcc
	s_cbranch_execz .LBB0_1088
	v_lshlrev_b64 v[34:35], 7, v[112:113]
	v_lshl_add_u64 v[34:35], s[14:15], 0, v[34:35]
	v_lshl_add_u64 v[34:35], s[40:41], 2, v[34:35]
	s_lshl_b32 s10, s55, 2
	v_lshl_add_u64 v[34:35], v[34:35], 0, s[10:11]
	s_waitcnt lgkmcnt(0)
	v_add_f32_e32 v32, v32, v33
	global_store_dword v[34:35], v32, off
.LBB0_1088:
	s_or_b64 exec, exec, s[42:43]
	v_or_b32_e32 v64, 48, v128
	v_ashrrev_i32_e32 v65, 31, v64
	v_readlane_b32 s64, v254, 2
	s_waitcnt lgkmcnt(0)
	v_lshlrev_b64 v[32:33], 13, v[64:65]
	v_readlane_b32 s65, v254, 3
	v_readlane_b32 s76, v254, 14
	v_readlane_b32 s77, v254, 15
	v_lshl_add_u64 v[32:33], s[64:65], 0, v[32:33]
	v_lshl_add_u64 v[36:37], v[170:171], 2, v[32:33]
	global_load_dwordx4 v[40:43], v[36:37], off offset:16 nt
	global_load_dwordx4 v[44:47], v[36:37], off nt
	global_load_dwordx4 v[32:35], v[36:37], off offset:528 nt
	s_nop 0
	global_load_dwordx4 v[36:39], v[36:37], off offset:512 nt
	v_readlane_b32 s78, v254, 16
	v_readlane_b32 s79, v254, 17
	v_lshlrev_b64 v[66:67], 11, v[96:97]
	v_readlane_b32 s76, v254, 56
	v_lshl_add_u64 v[66:67], v[66:67], 0, v[170:171]
	v_readlane_b32 s77, v254, 57
	s_waitcnt vmcnt(12)
	v_pk_fma_f32 v[30:31], v[30:31], v[86:87], v[62:63]
	v_pk_fma_f32 v[28:29], v[28:29], v[84:85], v[60:61]
	v_lshl_add_u64 v[60:61], v[66:67], 2, s[76:77]
	v_pk_fma_f32 v[26:27], v[26:27], v[82:83], v[58:59]
	v_pk_fma_f32 v[24:25], v[24:25], v[80:81], v[56:57]
	global_store_dwordx4 v[60:61], v[28:31], off
	global_store_dwordx4 v[60:61], v[24:27], off offset:16 nt
	v_pk_mul_f32 v[56:57], v[186:187], v[28:29]
	v_mul_f32_e32 v29, v29, v29
	v_fmac_f32_e32 v29, v28, v28
	v_mul_f32_e32 v28, v31, v31
	v_pk_mul_f32 v[58:59], v[184:185], v[30:31]
	v_pk_mul_f32 v[62:63], v[180:181], v[26:27]
	v_pk_mul_f32 v[68:69], v[182:183], v[24:25]
	v_fmac_f32_e32 v28, v30, v30
	v_mul_f32_e32 v25, v25, v25
	v_cvt_pk_bf16_f32 v56, v56, v57
	v_cvt_pk_bf16_f32 v57, v58, v59
	v_cvt_pk_bf16_f32 v59, v62, v63
	v_lshlrev_b64 v[62:63], 1, v[66:67]
	v_add_f32_e32 v28, v29, v28
	v_fmac_f32_e32 v25, v24, v24
	v_cvt_pk_bf16_f32 v58, v68, v69
	v_lshl_add_u64 v[66:67], s[86:87], 0, v[62:63]
	v_add_f32_e32 v24, v28, v25
	v_mul_f32_e32 v25, v27, v27
	s_waitcnt vmcnt(12)
	v_pk_fma_f32 v[22:23], v[22:23], v[94:95], v[54:55]
	v_pk_fma_f32 v[20:21], v[20:21], v[92:93], v[52:53]
	global_store_dwordx4 v[66:67], v[56:59], off sc1
	v_fmac_f32_e32 v25, v26, v26
	v_pk_fma_f32 v[18:19], v[18:19], v[90:91], v[50:51]
	v_pk_fma_f32 v[16:17], v[16:17], v[88:89], v[48:49]
	global_store_dwordx4 v[60:61], v[20:23], off offset:512 nt
	global_store_dwordx4 v[60:61], v[16:19], off offset:528 nt
	v_pk_mul_f32 v[26:27], v[178:179], v[20:21]
	v_mul_f32_e32 v21, v21, v21
	v_fmac_f32_e32 v21, v20, v20
	v_mul_f32_e32 v20, v23, v23
	v_fmac_f32_e32 v20, v22, v22
	v_add_f32_e32 v20, v21, v20
	v_mul_f32_e32 v21, v17, v17
	v_pk_mul_f32 v[28:29], v[174:175], v[18:19]
	v_fmac_f32_e32 v21, v16, v16
	v_mul_f32_e32 v19, v19, v19
	v_add_f32_e32 v20, v20, v21
	v_fmac_f32_e32 v19, v18, v18
	v_add_f32_e32 v30, v25, v24
	v_add_f32_e32 v18, v19, v20
	v_add_f32_e32 v21, v30, v18
	v_pk_mul_f32 v[24:25], v[176:177], v[22:23]
	ds_bpermute_b32 v22, v202, v21
	v_pk_mul_f32 v[16:17], v[172:173], v[16:17]
	v_or_b32_e32 v62, 0x100, v62
	v_cvt_pk_bf16_f32 v20, v16, v17
	v_readlane_b32 s78, v254, 58
	s_waitcnt lgkmcnt(0)
	v_add_f32_e32 v16, v21, v22
	ds_bpermute_b32 v17, v201, v16
	v_readlane_b32 s79, v254, 59
	v_cvt_pk_bf16_f32 v18, v26, v27
	v_cvt_pk_bf16_f32 v19, v24, v25
	v_cvt_pk_bf16_f32 v21, v28, v29
	v_lshl_add_u64 v[22:23], s[86:87], 0, v[62:63]
	v_readlane_b32 s66, v254, 4
	v_readlane_b32 s67, v254, 5
	v_readlane_b32 s68, v254, 6
	v_readlane_b32 s69, v254, 7
	v_readlane_b32 s70, v254, 8
	v_readlane_b32 s71, v254, 9
	v_readlane_b32 s72, v254, 10
	v_readlane_b32 s73, v254, 11
	v_readlane_b32 s74, v254, 12
	v_readlane_b32 s75, v254, 13
	global_store_dwordx4 v[22:23], v[18:21], off sc1
	s_and_saveexec_b64 s[42:43], vcc
	s_cbranch_execz .LBB0_1090
	v_lshlrev_b64 v[18:19], 7, v[96:97]
	v_lshl_add_u64 v[18:19], s[14:15], 0, v[18:19]
	v_lshl_add_u64 v[18:19], s[40:41], 2, v[18:19]
	s_lshl_b32 s10, s55, 2
	v_lshl_add_u64 v[18:19], v[18:19], 0, s[10:11]
	s_waitcnt lgkmcnt(0)
	v_add_f32_e32 v16, v16, v17
	global_store_dword v[18:19], v16, off
.LBB0_1090:
	s_or_b64 exec, exec, s[42:43]
	s_waitcnt lgkmcnt(0)
	v_lshlrev_b64 v[16:17], 11, v[64:65]
	v_lshl_add_u64 v[20:21], v[16:17], 0, v[170:171]
	s_waitcnt vmcnt(8)
	v_pk_fma_f32 v[14:15], v[14:15], v[86:87], v[46:47]
	v_pk_fma_f32 v[12:13], v[12:13], v[84:85], v[44:45]
	v_lshl_add_u64 v[22:23], v[20:21], 2, s[76:77]
	v_pk_fma_f32 v[10:11], v[10:11], v[82:83], v[42:43]
	v_pk_fma_f32 v[8:9], v[8:9], v[80:81], v[40:41]
	global_store_dwordx4 v[22:23], v[12:15], off
	global_store_dwordx4 v[22:23], v[8:11], off offset:16 nt
	v_pk_mul_f32 v[16:17], v[186:187], v[12:13]
	v_mul_f32_e32 v13, v13, v13
	v_fmac_f32_e32 v13, v12, v12
	v_mul_f32_e32 v12, v15, v15
	v_pk_mul_f32 v[26:27], v[182:183], v[8:9]
	v_fmac_f32_e32 v12, v14, v14
	v_mul_f32_e32 v9, v9, v9
	v_pk_mul_f32 v[18:19], v[184:185], v[14:15]
	v_pk_mul_f32 v[24:25], v[180:181], v[10:11]
	v_lshlrev_b64 v[20:21], 1, v[20:21]
	v_add_f32_e32 v12, v13, v12
	v_fmac_f32_e32 v9, v8, v8
	v_cvt_pk_bf16_f32 v16, v16, v17
	v_cvt_pk_bf16_f32 v17, v18, v19
	v_cvt_pk_bf16_f32 v18, v26, v27
	v_cvt_pk_bf16_f32 v19, v24, v25
	v_lshl_add_u64 v[24:25], s[86:87], 0, v[20:21]
	v_add_f32_e32 v8, v12, v9
	v_mul_f32_e32 v9, v11, v11
	s_waitcnt vmcnt(8)
	v_pk_fma_f32 v[6:7], v[6:7], v[94:95], v[38:39]
	v_pk_fma_f32 v[4:5], v[4:5], v[92:93], v[36:37]
	global_store_dwordx4 v[24:25], v[16:19], off sc1
	v_fmac_f32_e32 v9, v10, v10
	v_pk_fma_f32 v[2:3], v[2:3], v[90:91], v[34:35]
	v_pk_fma_f32 v[0:1], v[0:1], v[88:89], v[32:33]
	global_store_dwordx4 v[22:23], v[4:7], off offset:512 nt
	global_store_dwordx4 v[22:23], v[0:3], off offset:528 nt
	v_pk_mul_f32 v[10:11], v[178:179], v[4:5]
	v_mul_f32_e32 v5, v5, v5
	v_fmac_f32_e32 v5, v4, v4
	v_mul_f32_e32 v4, v7, v7
	v_fmac_f32_e32 v4, v6, v6
	v_add_f32_e32 v4, v5, v4
	v_mul_f32_e32 v5, v1, v1
	v_pk_mul_f32 v[12:13], v[174:175], v[2:3]
	v_fmac_f32_e32 v5, v0, v0
	v_mul_f32_e32 v3, v3, v3
	v_add_f32_e32 v4, v4, v5
	v_fmac_f32_e32 v3, v2, v2
	v_add_f32_e32 v14, v9, v8
	v_add_f32_e32 v2, v3, v4
	v_add_f32_e32 v5, v14, v2
	v_pk_mul_f32 v[8:9], v[176:177], v[6:7]
	ds_bpermute_b32 v6, v202, v5
	v_pk_mul_f32 v[0:1], v[172:173], v[0:1]
	v_or_b32_e32 v20, 0x100, v20
	v_cvt_pk_bf16_f32 v4, v0, v1
	v_cvt_pk_bf16_f32 v2, v10, v11
	s_waitcnt lgkmcnt(0)
	v_add_f32_e32 v0, v5, v6
	ds_bpermute_b32 v1, v201, v0
	v_cvt_pk_bf16_f32 v3, v8, v9
	v_cvt_pk_bf16_f32 v5, v12, v13
	v_lshl_add_u64 v[6:7], s[86:87], 0, v[20:21]
	global_store_dwordx4 v[6:7], v[2:5], off sc1
	s_and_saveexec_b64 s[42:43], vcc
	s_cbranch_execz .LBB0_1092
	v_lshlrev_b64 v[2:3], 7, v[64:65]
	v_lshl_add_u64 v[2:3], s[14:15], 0, v[2:3]
	v_lshl_add_u64 v[2:3], s[40:41], 2, v[2:3]
	s_lshl_b32 s10, s55, 2
	v_lshl_add_u64 v[2:3], v[2:3], 0, s[10:11]
	s_waitcnt lgkmcnt(0)
	v_add_f32_e32 v0, v0, v1
	global_store_dword v[2:3], v0, off
